# attention O stores widened to dwordx4 via v_permlane32_swap pairs and made write-through (sc1)
# baseline (speedup 1.0000x reference)
.LBB0_186:
	v_and_b32_e32 v2, 64, v203
	v_xor_b32_e32 v1, 32, v203
	v_add_u32_e32 v2, 64, v2
	v_cmp_lt_i32_e32 vcc, v1, v2
	s_lshl_b32 s4, s3, 7
	s_nop 0
	v_cndmask_b32_e32 v1, v203, v1, vcc
	v_lshlrev_b32_e32 v1, 2, v1
	ds_bpermute_b32 v1, v1, v48
	s_waitcnt lgkmcnt(0)
	v_add_f32_e32 v1, v48, v1
	v_div_scale_f32 v2, s[0:1], v1, v1, 1.0
	v_rcp_f32_e32 v3, v2
	v_readlane_b32 s0, v253, 27
	v_readlane_b32 s1, v253, 28
	v_fma_f32 v4, -v2, v3, 1.0
	v_fmac_f32_e32 v3, v4, v3
	v_div_scale_f32 v4, vcc, 1.0, v1, 1.0
	v_mul_f32_e32 v5, v4, v3
	v_fma_f32 v6, -v2, v5, v4
	v_fmac_f32_e32 v5, v6, v3
	v_fma_f32 v2, -v2, v5, v4
	v_div_fmas_f32 v2, v2, v3, v5
	v_mov_b64_e32 v[4:5], s[0:1]
	v_div_fixup_f32 v2, v2, v1, 1.0
	v_mad_i64_i32 v[4:5], s[0:1], v194, s19, v[4:5]
	v_lshl_add_u64 v[4:5], v[4:5], 0, s[4:5]
	v_lshl_add_u64 v[4:5], v[178:179], 1, v[4:5]
	v_and_b32_e32 v12, 32, v203
	v_lshrrev_b32_e32 v12, 2, v12
	v_mov_b32_e32 v13, v0
	v_lshl_add_u64 v[4:5], v[12:13], 0, v[4:5]
	v_pk_mul_f32 v[12:13], v[32:33], v[2:3] op_sel_hi:[1,0]
	v_pk_mul_f32 v[14:15], v[34:35], v[2:3] op_sel_hi:[1,0]
	v_pk_mul_f32 v[50:51], v[36:37], v[2:3] op_sel_hi:[1,0]
	v_pk_mul_f32 v[52:53], v[38:39], v[2:3] op_sel_hi:[1,0]
	v_cvt_pk_bf16_f32 v8, v12, v13
	v_cvt_pk_bf16_f32 v9, v14, v15
	v_cvt_pk_bf16_f32 v10, v50, v51
	v_cvt_pk_bf16_f32 v11, v52, v53
	s_nop 1
	v_permlane32_swap_b32_e32 v8, v10
	v_permlane32_swap_b32_e32 v9, v11
	global_store_dwordx4 v[4:5], v[8:11], off sc1
	v_pk_mul_f32 v[12:13], v[40:41], v[2:3] op_sel_hi:[1,0]
	v_pk_mul_f32 v[14:15], v[42:43], v[2:3] op_sel_hi:[1,0]
	v_pk_mul_f32 v[50:51], v[44:45], v[2:3] op_sel_hi:[1,0]
	v_pk_mul_f32 v[52:53], v[46:47], v[2:3] op_sel_hi:[1,0]
	v_cvt_pk_bf16_f32 v8, v12, v13
	v_cvt_pk_bf16_f32 v9, v14, v15
	v_cvt_pk_bf16_f32 v10, v50, v51
	v_cvt_pk_bf16_f32 v11, v52, v53
	s_nop 1
	v_permlane32_swap_b32_e32 v8, v10
	v_permlane32_swap_b32_e32 v9, v11
	global_store_dwordx4 v[4:5], v[8:11], off offset:32 sc1
	v_pk_mul_f32 v[12:13], v[16:17], v[2:3] op_sel_hi:[1,0]
	v_pk_mul_f32 v[14:15], v[18:19], v[2:3] op_sel_hi:[1,0]
	v_pk_mul_f32 v[50:51], v[20:21], v[2:3] op_sel_hi:[1,0]
	v_pk_mul_f32 v[52:53], v[22:23], v[2:3] op_sel_hi:[1,0]
	v_cvt_pk_bf16_f32 v8, v12, v13
	v_cvt_pk_bf16_f32 v9, v14, v15
	v_cvt_pk_bf16_f32 v10, v50, v51
	v_cvt_pk_bf16_f32 v11, v52, v53
	s_nop 1
	v_permlane32_swap_b32_e32 v8, v10
	v_permlane32_swap_b32_e32 v9, v11
	global_store_dwordx4 v[4:5], v[8:11], off offset:64 sc1
	v_pk_mul_f32 v[12:13], v[24:25], v[2:3] op_sel_hi:[1,0]
	v_pk_mul_f32 v[14:15], v[26:27], v[2:3] op_sel_hi:[1,0]
	v_pk_mul_f32 v[50:51], v[28:29], v[2:3] op_sel_hi:[1,0]
	v_pk_mul_f32 v[52:53], v[30:31], v[2:3] op_sel_hi:[1,0]
	v_cvt_pk_bf16_f32 v8, v12, v13
	v_cvt_pk_bf16_f32 v9, v14, v15
	v_cvt_pk_bf16_f32 v10, v50, v51
	v_cvt_pk_bf16_f32 v11, v52, v53
	s_nop 1
	v_permlane32_swap_b32_e32 v8, v10
	v_permlane32_swap_b32_e32 v9, v11
	global_store_dwordx4 v[4:5], v[8:11], off offset:96 sc1
	s_waitcnt lgkmcnt(0)
	s_branch .LBB0_145

.LBB0_242:
	v_div_scale_f32 v2, s[20:21], v1, v1, 1.0
	v_rcp_f32_e32 v3, v2
	v_div_scale_f32 v4, vcc, 1.0, v1, 1.0
	v_fma_f32 v5, -v2, v3, 1.0
	v_fmac_f32_e32 v3, v5, v3
	v_mul_f32_e32 v5, v4, v3
	v_fma_f32 v6, -v2, v5, v4
	v_fmac_f32_e32 v5, v6, v3
	v_fma_f32 v2, -v2, v5, v4
	v_div_fmas_f32 v2, v2, v3, v5
	v_div_fixup_f32 v2, v2, v1, 1.0
	v_mad_i64_i32 v[4:5], s[20:21], v196, s19, v[190:191]
	v_and_b32_e32 v12, 32, v203
	v_lshrrev_b32_e32 v12, 2, v12
	v_mov_b32_e32 v13, v0
	v_lshl_add_u64 v[4:5], v[12:13], 0, v[4:5]
	v_pk_mul_f32 v[12:13], v[32:33], v[2:3] op_sel_hi:[1,0]
	v_pk_mul_f32 v[14:15], v[34:35], v[2:3] op_sel_hi:[1,0]
	v_pk_mul_f32 v[48:49], v[36:37], v[2:3] op_sel_hi:[1,0]
	v_pk_mul_f32 v[50:51], v[38:39], v[2:3] op_sel_hi:[1,0]
	v_cvt_pk_bf16_f32 v8, v12, v13
	v_cvt_pk_bf16_f32 v9, v14, v15
	v_cvt_pk_bf16_f32 v10, v48, v49
	v_cvt_pk_bf16_f32 v11, v50, v51
	s_nop 1
	v_permlane32_swap_b32_e32 v8, v10
	v_permlane32_swap_b32_e32 v9, v11
	global_store_dwordx4 v[4:5], v[8:11], off offset:1024 sc1
	v_pk_mul_f32 v[12:13], v[40:41], v[2:3] op_sel_hi:[1,0]
	v_pk_mul_f32 v[14:15], v[42:43], v[2:3] op_sel_hi:[1,0]
	v_pk_mul_f32 v[48:49], v[44:45], v[2:3] op_sel_hi:[1,0]
	v_pk_mul_f32 v[50:51], v[46:47], v[2:3] op_sel_hi:[1,0]
	v_cvt_pk_bf16_f32 v8, v12, v13
	v_cvt_pk_bf16_f32 v9, v14, v15
	v_cvt_pk_bf16_f32 v10, v48, v49
	v_cvt_pk_bf16_f32 v11, v50, v51
	s_nop 1
	v_permlane32_swap_b32_e32 v8, v10
	v_permlane32_swap_b32_e32 v9, v11
	global_store_dwordx4 v[4:5], v[8:11], off offset:1056 sc1
	v_pk_mul_f32 v[12:13], v[16:17], v[2:3] op_sel_hi:[1,0]
	v_pk_mul_f32 v[14:15], v[18:19], v[2:3] op_sel_hi:[1,0]
	v_pk_mul_f32 v[48:49], v[20:21], v[2:3] op_sel_hi:[1,0]
	v_pk_mul_f32 v[50:51], v[22:23], v[2:3] op_sel_hi:[1,0]
	v_cvt_pk_bf16_f32 v8, v12, v13
	v_cvt_pk_bf16_f32 v9, v14, v15
	v_cvt_pk_bf16_f32 v10, v48, v49
	v_cvt_pk_bf16_f32 v11, v50, v51
	s_nop 1
	v_permlane32_swap_b32_e32 v8, v10
	v_permlane32_swap_b32_e32 v9, v11
	global_store_dwordx4 v[4:5], v[8:11], off offset:1088 sc1
	v_pk_mul_f32 v[12:13], v[24:25], v[2:3] op_sel_hi:[1,0]
	v_pk_mul_f32 v[14:15], v[26:27], v[2:3] op_sel_hi:[1,0]
	v_pk_mul_f32 v[48:49], v[28:29], v[2:3] op_sel_hi:[1,0]
	v_pk_mul_f32 v[50:51], v[30:31], v[2:3] op_sel_hi:[1,0]
	v_cvt_pk_bf16_f32 v8, v12, v13
	v_cvt_pk_bf16_f32 v9, v14, v15
	v_cvt_pk_bf16_f32 v10, v48, v49
	v_cvt_pk_bf16_f32 v11, v50, v51
	s_nop 1
	v_permlane32_swap_b32_e32 v8, v10
	v_permlane32_swap_b32_e32 v9, v11
	global_store_dwordx4 v[4:5], v[8:11], off offset:1120 sc1
	s_branch .LBB0_202
